# LDS parameter tables of the first up-GEMM unit of each phase prefetched in the phase prologue (no slow path in the first epilogue)
# speedup vs baseline: 1.0030x; 1.0017x over previous
.LBB0_822:
	v_lshrrev_b32_e32 v16, 1, v14
	v_and_b32_e32 v16, 24, v16
	s_add_u32 s14, s70, 0x3b00000
	v_and_b32_e32 v15, 15, v14
	v_lshlrev_b32_e32 v17, 1, v16
	v_lshlrev_b32_e32 v14, 2, v14
	s_sext_i32_i16 s66, s4
	s_addc_u32 s15, s71, 0
	v_lshl_or_b32 v170, s7, 6, v15
	v_lshl_or_b32 v15, v15, 6, v17
	s_lshl_b32 s4, s7, 13
	v_and_b32_e32 v14, 32, v14
	v_bitop3_b32 v17, v15, s4, v14 bitop3:0xde
	s_lshl_b32 s4, s6, 5
	s_mov_b64 s[16:17], 0x80
	s_and_b32 s4, s4, 0x60
	s_add_i32 m0, s31, 0x18000
	v_lshl_add_u64 v[6:7], v[6:7], 0, s[16:17]
	s_lshl_b32 s6, s4, 7
	s_waitcnt vmcnt(2)
	s_barrier
	global_load_lds_dwordx4 v[6:7], off
	v_lshl_add_u64 v[4:5], v[4:5], 0, s[16:17]
	s_add_i32 m0, s31, 0x1a000
	s_add_i32 s60, s31, 0x8000
	s_add_i32 s61, s31, 0xa000
	v_bitop3_b32 v171, v15, s6, v14 bitop3:0xde
	global_load_lds_dwordx4 v[4:5], off
	v_lshl_add_u64 v[0:1], v[0:1], 0, s[16:17]
	s_mov_b32 m0, s60
	s_add_u32 s6, s92, 0x580080
	global_load_lds_dwordx4 v[0:1], off
	v_lshl_add_u64 v[0:1], v[2:3], 0, s[16:17]
	s_mov_b32 m0, s61
	s_addc_u32 s7, s93, 0
	global_load_lds_dwordx4 v[0:1], off
	s_add_i32 m0, s31, 0x1c000
	v_lshl_add_u64 v[0:1], s[6:7], 0, v[148:149]
	global_load_lds_dwordx4 v[0:1], off
	v_lshl_add_u64 v[0:1], s[6:7], 0, v[144:145]
	s_add_i32 m0, s31, 0x1e000
	s_cmpk_lt_u32 s5, 0x100
	global_load_lds_dwordx4 v[0:1], off
	v_lshlrev_b32_e32 v0, 14, v12
	v_and_b32_e32 v0, 0xffff8000, v0
	v_lshl_add_u32 v0, v11, 11, v0
	v_and_b32_e32 v1, 1, v12
	v_lshl_or_b32 v0, v1, 6, v0
	v_lshl_add_u32 v152, v13, 1, v0
	v_lshrrev_b32_e32 v248, 11, v152
	v_and_b32_e32 v249, 0x7ff, v152
	v_and_b32_e32 v250, 15, v248
	v_lshlrev_b32_e32 v250, 2, v250
	v_bfe_u32 v251, v248, 4, 2
	v_and_or_b32 v248, v248, 64, v250
	v_or_b32_e32 v248, v248, v251
	v_lshl_or_b32 v152, v248, 11, v249
	v_lshlrev_b32_e32 v0, 14, v8
	v_and_b32_e32 v0, 0xffff8000, v0
	s_waitcnt vmcnt(6)
	v_lshl_add_u32 v0, v9, 11, v0
	v_and_b32_e32 v1, 1, v8
	s_cselect_b64 s[34:35], -1, 0
	v_lshl_or_b32 v0, v1, 6, v0
	s_add_i32 s62, 0, 0x10000
	s_add_i32 s63, 0, 0x14000
	v_or_b32_e32 v172, s4, v16
	v_mov_b32_e32 v153, v149
	v_lshl_add_u32 v154, v10, 1, v0
	v_lshrrev_b32_e32 v248, 11, v154
	v_and_b32_e32 v249, 0x7ff, v154
	v_and_b32_e32 v250, 15, v248
	v_lshlrev_b32_e32 v250, 2, v250
	v_bfe_u32 v251, v248, 4, 2
	v_and_or_b32 v248, v248, 64, v250
	v_or_b32_e32 v248, v248, v251
	v_lshl_or_b32 v154, v248, 11, v249
	v_mov_b32_e32 v155, v149
	v_mov_b64_e32 v[156:157], 0x2c0
	v_mov_b64_e32 v[158:159], 0x2bf
	v_add_u32_e32 v173, s62, v171
	v_add_u32_e32 v174, s63, v171
	v_add_u32_e32 v175, 0, v17
	v_mov_b32_e32 v176, 0x358637bd
	s_mov_b32 s64, 0x800000
	s_movk_i32 s65, 0x2c00
	s_barrier
	s_mov_b32 s101, 2
	s_mov_b32 s32, 0x22c00
	v_readfirstlane_b32 s28, v230
	s_cmp_lt_u32 s28, 64
	s_cbranch_scc0 .LpreB_nf
	s_add_i32 s2, s88, -32
	s_ashr_i32 s2, s2, 2
	s_add_i32 s2, s2, 1
	s_cmp_gt_i32 s88, 31
	s_cselect_b32 s2, s2, 0
	s_mul_hi_i32 s3, s2, 0x5800
	s_mulk_i32 s2, 0x5800
	v_readlane_b32 s28, v254, 49
	v_readlane_b32 s29, v254, 50
	s_nop 0
	s_add_u32 s2, s28, s2
	s_addc_u32 s3, s29, s3
	v_readlane_b32 s4, v254, 5
	v_readlane_b32 s5, v254, 6
	v_readlane_b32 s6, v254, 7
	v_readlane_b32 s7, v254, 8
	s_nop 0
	v_and_b32_e32 v240, 63, v230
	v_lshrrev_b32_e32 v241, 5, v240
	v_and_b32_e32 v242, 31, v240
	v_lshlrev_b32_e32 v242, 4, v242
	s_lshl_b32 s28, s66, 9
	v_add_u32_e32 v242, s28, v242
	v_mul_u32_u24_e32 v243, 0x2c00, v241
	v_mul_u32_u24_e32 v244, 0x5800, v241
	v_add_u32_e32 v243, v243, v242
	v_add_u32_e32 v244, v244, v242
	v_lshlrev_b32_e32 v245, 4, v240
	s_lshl_b32 s28, s88, 10
	v_add_u32_e32 v245, s28, v245
	s_mov_b32 m0, s32
	s_nop 0
	global_load_lds_dwordx4 v245, s[10:11]
	s_add_i32 m0, s32, 1024
	s_nop 0
	global_load_lds_dwordx4 v243, s[2:3]
	s_add_i32 m0, s32, 2048
	s_nop 0
	global_load_lds_dwordx4 v244, s[4:5]
	v_add_u32_e32 v245, 0x2c00, v244
	s_add_i32 m0, s32, 3072
	s_nop 0
	global_load_lds_dwordx4 v245, s[4:5]
	v_add_u32_e32 v245, 0xb000, v243
	s_add_i32 m0, s32, 4096
	s_nop 0
	global_load_lds_dwordx4 v245, s[4:5]
	s_add_i32 m0, s32, 5120
	s_nop 0
	global_load_lds_dwordx4 v243, s[6:7]
.LpreB_nf:
	s_branch .LBB0_825

.LBB0_961:
	s_add_u32 s12, s70, 0x108000
	v_lshrrev_b32_e32 v16, 1, v14
	s_addc_u32 s13, s71, 0
	v_and_b32_e32 v16, 24, v16
	s_add_u32 s14, s70, 0x3b00000
	v_and_b32_e32 v15, 15, v14
	v_lshlrev_b32_e32 v17, 1, v16
	v_lshlrev_b32_e32 v14, 2, v14
	s_sext_i32_i16 s66, s4
	s_addc_u32 s15, s71, 0
	v_lshl_or_b32 v170, s7, 6, v15
	v_lshl_or_b32 v15, v15, 6, v17
	s_lshl_b32 s4, s7, 13
	v_and_b32_e32 v14, 32, v14
	v_bitop3_b32 v17, v15, s4, v14 bitop3:0xde
	s_lshl_b32 s4, s6, 5
	s_mov_b64 s[16:17], 0x80
	s_and_b32 s4, s4, 0x60
	s_add_i32 m0, s31, 0x18000
	v_lshl_add_u64 v[6:7], v[6:7], 0, s[16:17]
	s_lshl_b32 s6, s4, 7
	s_waitcnt vmcnt(2)
	s_barrier
	global_load_lds_dwordx4 v[6:7], off
	v_lshl_add_u64 v[4:5], v[4:5], 0, s[16:17]
	s_add_i32 m0, s31, 0x1a000
	s_add_i32 s60, s31, 0x8000
	s_add_i32 s61, s31, 0xa000
	v_bitop3_b32 v171, v15, s6, v14 bitop3:0xde
	global_load_lds_dwordx4 v[4:5], off
	v_lshl_add_u64 v[0:1], v[0:1], 0, s[16:17]
	s_mov_b32 m0, s60
	s_add_u32 s6, s92, 0x580080
	global_load_lds_dwordx4 v[0:1], off
	v_lshl_add_u64 v[0:1], v[2:3], 0, s[16:17]
	s_mov_b32 m0, s61
	s_addc_u32 s7, s93, 0
	global_load_lds_dwordx4 v[0:1], off
	s_add_i32 m0, s31, 0x1c000
	v_lshl_add_u64 v[0:1], s[6:7], 0, v[148:149]
	global_load_lds_dwordx4 v[0:1], off
	v_lshl_add_u64 v[0:1], s[6:7], 0, v[144:145]
	s_add_i32 m0, s31, 0x1e000
	s_cmpk_lt_u32 s5, 0x100
	global_load_lds_dwordx4 v[0:1], off
	v_lshlrev_b32_e32 v0, 14, v12
	v_and_b32_e32 v0, 0xffff8000, v0
	v_lshl_add_u32 v0, v11, 11, v0
	v_and_b32_e32 v1, 1, v12
	v_lshl_or_b32 v0, v1, 6, v0
	v_lshl_add_u32 v152, v13, 1, v0
	v_lshrrev_b32_e32 v248, 11, v152
	v_and_b32_e32 v249, 0x7ff, v152
	v_and_b32_e32 v250, 15, v248
	v_lshlrev_b32_e32 v250, 2, v250
	v_bfe_u32 v251, v248, 4, 2
	v_and_or_b32 v248, v248, 64, v250
	v_or_b32_e32 v248, v248, v251
	v_lshl_or_b32 v152, v248, 11, v249
	v_lshlrev_b32_e32 v0, 14, v8
	v_and_b32_e32 v0, 0xffff8000, v0
	s_waitcnt vmcnt(6)
	v_lshl_add_u32 v0, v9, 11, v0
	v_and_b32_e32 v1, 1, v8
	s_cselect_b64 s[34:35], -1, 0
	v_lshl_or_b32 v0, v1, 6, v0
	s_add_i32 s62, 0, 0x10000
	s_add_i32 s63, 0, 0x14000
	v_or_b32_e32 v172, s4, v16
	v_mov_b32_e32 v153, v149
	v_lshl_add_u32 v154, v10, 1, v0
	v_lshrrev_b32_e32 v248, 11, v154
	v_and_b32_e32 v249, 0x7ff, v154
	v_and_b32_e32 v250, 15, v248
	v_lshlrev_b32_e32 v250, 2, v250
	v_bfe_u32 v251, v248, 4, 2
	v_and_or_b32 v248, v248, 64, v250
	v_or_b32_e32 v248, v248, v251
	v_lshl_or_b32 v154, v248, 11, v249
	v_mov_b32_e32 v155, v149
	v_mov_b64_e32 v[156:157], 0x2c0
	v_mov_b64_e32 v[158:159], 0x2bf
	v_add_u32_e32 v173, s62, v171
	v_add_u32_e32 v174, s63, v171
	v_add_u32_e32 v175, 0, v17
	v_mov_b32_e32 v176, 0x358637bd
	s_mov_b32 s64, 0x800000
	s_movk_i32 s65, 0x2c00
	s_barrier
	s_mov_b32 s101, 2
	s_mov_b32 s32, 0x22c00
	v_readfirstlane_b32 s28, v230
	s_cmp_lt_u32 s28, 64
	s_cbranch_scc0 .LpreD_nf
	s_add_i32 s2, s88, 0
	s_ashr_i32 s2, s2, 2
	s_add_i32 s2, s2, 1
	s_cmp_gt_i32 s88, -1
	s_cselect_b32 s2, s2, 0
	s_mul_hi_i32 s3, s2, 0x5800
	s_mulk_i32 s2, 0x5800
	v_readlane_b32 s28, v254, 49
	v_readlane_b32 s29, v254, 50
	s_nop 0
	s_add_u32 s2, s28, s2
	s_addc_u32 s3, s29, s3
	v_readlane_b32 s4, v254, 5
	v_readlane_b32 s5, v254, 6
	v_readlane_b32 s6, v254, 7
	v_readlane_b32 s7, v254, 8
	s_nop 0
	v_and_b32_e32 v240, 63, v230
	v_lshrrev_b32_e32 v241, 5, v240
	v_and_b32_e32 v242, 31, v240
	v_lshlrev_b32_e32 v242, 4, v242
	s_lshl_b32 s28, s66, 9
	v_add_u32_e32 v242, s28, v242
	v_mul_u32_u24_e32 v243, 0x2c00, v241
	v_mul_u32_u24_e32 v244, 0x5800, v241
	v_add_u32_e32 v243, v243, v242
	v_add_u32_e32 v244, v244, v242
	v_lshlrev_b32_e32 v245, 4, v240
	s_lshl_b32 s28, s88, 10
	v_add_u32_e32 v245, s28, v245
	s_mov_b32 m0, s32
	s_nop 0
	global_load_lds_dwordx4 v245, s[12:13]
	s_add_i32 m0, s32, 1024
	s_nop 0
	global_load_lds_dwordx4 v243, s[2:3]
	s_add_i32 m0, s32, 2048
	s_nop 0
	global_load_lds_dwordx4 v244, s[4:5]
	v_add_u32_e32 v245, 0x2c00, v244
	s_add_i32 m0, s32, 3072
	s_nop 0
	global_load_lds_dwordx4 v245, s[4:5]
	v_add_u32_e32 v245, 0xb000, v243
	s_add_i32 m0, s32, 4096
	s_nop 0
	global_load_lds_dwordx4 v245, s[4:5]
	s_add_i32 m0, s32, 5120
	s_nop 0
	global_load_lds_dwordx4 v243, s[6:7]

.LBB0_1746:
	s_add_u32 s14, s70, 0x3b00000
	s_addc_u32 s15, s71, 0
	s_lshl_b32 s7, s7, 5
	s_mov_b64 s[16:17], 0x80
	s_and_b32 s7, s7, 0x60
	s_add_i32 m0, s42, 0x18000
	v_lshl_add_u64 v[6:7], v[6:7], 0, s[16:17]
	s_lshl_b32 s24, s5, 13
	s_lshl_b32 s25, s7, 7
	s_waitcnt vmcnt(2)
	s_barrier
	global_load_lds_dwordx4 v[6:7], off
	v_lshl_add_u64 v[4:5], v[4:5], 0, s[16:17]
	s_add_i32 m0, s42, 0x1a000
	s_add_i32 s47, s42, 0x8000
	s_add_i32 s48, s42, 0xa000
	global_load_lds_dwordx4 v[4:5], off
	v_lshl_add_u64 v[0:1], v[0:1], 0, s[16:17]
	s_mov_b32 m0, s47
	s_add_u32 s22, s38, 0x580080
	global_load_lds_dwordx4 v[0:1], off
	v_lshl_add_u64 v[0:1], v[2:3], 0, s[16:17]
	s_mov_b32 m0, s48
	s_addc_u32 s23, s39, 0
	global_load_lds_dwordx4 v[0:1], off
	s_add_i32 m0, s42, 0x1c000
	v_lshl_add_u64 v[0:1], s[22:23], 0, v[148:149]
	global_load_lds_dwordx4 v[0:1], off
	v_lshl_add_u64 v[0:1], s[22:23], 0, v[144:145]
	s_add_i32 m0, s42, 0x1e000
	s_cmpk_lt_u32 s4, 0x100
	global_load_lds_dwordx4 v[0:1], off
	v_lshrrev_b32_e32 v1, 1, v9
	v_and_b32_e32 v1, 24, v1
	v_and_b32_e32 v0, 15, v9
	v_lshlrev_b32_e32 v2, 1, v1
	v_lshl_or_b32 v164, s5, 6, v0
	v_lshl_or_b32 v0, v0, 6, v2
	v_lshlrev_b32_e32 v2, 2, v9
	v_and_b32_e32 v2, 32, v2
	v_bitop3_b32 v3, v0, s24, v2 bitop3:0xde
	v_bitop3_b32 v165, v0, s25, v2 bitop3:0xde
	v_lshlrev_b32_e32 v0, 14, v13
	v_and_b32_e32 v0, 0xffff8000, v0
	v_or_b32_e32 v166, s7, v1
	v_lshl_add_u32 v0, v12, 11, v0
	v_and_b32_e32 v1, 1, v13
	v_lshl_or_b32 v0, v1, 6, v0
	v_lshl_add_u32 v152, v14, 1, v0
	v_lshrrev_b32_e32 v248, 11, v152
	v_and_b32_e32 v249, 0x7ff, v152
	v_and_b32_e32 v250, 15, v248
	v_lshlrev_b32_e32 v250, 2, v250
	v_bfe_u32 v251, v248, 4, 2
	v_and_or_b32 v248, v248, 64, v250
	v_or_b32_e32 v248, v248, v251
	v_lshl_or_b32 v152, v248, 11, v249
	v_lshlrev_b32_e32 v0, 14, v8
	v_and_b32_e32 v0, 0xffff8000, v0
	s_waitcnt vmcnt(6)
	v_lshl_add_u32 v0, v10, 11, v0
	v_and_b32_e32 v1, 1, v8
	s_cselect_b64 s[22:23], -1, 0
	v_lshl_or_b32 v0, v1, 6, v0
	s_add_i32 s49, 0, 0x10000
	s_add_i32 s51, 0, 0x14000
	s_sext_i32_i16 s9, s6
	v_mov_b32_e32 v153, v149
	v_lshl_add_u32 v154, v11, 1, v0
	v_lshrrev_b32_e32 v248, 11, v154
	v_and_b32_e32 v249, 0x7ff, v154
	v_and_b32_e32 v250, 15, v248
	v_lshlrev_b32_e32 v250, 2, v250
	v_bfe_u32 v251, v248, 4, 2
	v_and_or_b32 v248, v248, 64, v250
	v_or_b32_e32 v248, v248, v251
	v_lshl_or_b32 v154, v248, 11, v249
	v_mov_b32_e32 v155, v149
	v_mov_b64_e32 v[156:157], 0x2c0
	v_mov_b64_e32 v[158:159], 0x2bf
	v_add_u32_e32 v167, s49, v165
	v_add_u32_e32 v168, s51, v165
	v_add_u32_e32 v169, 0, v3
	v_mov_b32_e32 v170, 0x358637bd
	s_mov_b32 s52, 0x800000
	s_movk_i32 s53, 0x2c00
	s_barrier
	s_mov_b32 s101, 2
	s_mov_b32 s28, 0x22c00
	v_readfirstlane_b32 s25, v230
	s_cmp_lt_u32 s25, 64
	s_cbranch_scc0 .LpreA_nf
	s_add_i32 s4, s8, -32
	s_ashr_i32 s4, s4, 2
	s_add_i32 s4, s4, 1
	s_cmp_gt_i32 s8, 31
	s_cselect_b32 s4, s4, 0
	s_mul_hi_i32 s5, s4, 0x5800
	s_mulk_i32 s4, 0x5800
	s_add_u32 s4, s33, s4
	s_addc_u32 s5, s50, s5
	v_readlane_b32 s6, v254, 5
	v_readlane_b32 s7, v254, 6
	v_readlane_b32 s14, v254, 7
	v_readlane_b32 s15, v254, 8
	s_nop 0
	s_add_u32 s6, s6, 0x10800
	s_addc_u32 s7, s7, 0
	s_add_u32 s14, s14, 0x5800
	s_addc_u32 s15, s15, 0
	v_and_b32_e32 v240, 63, v230
	v_lshrrev_b32_e32 v241, 5, v240
	v_and_b32_e32 v242, 31, v240
	v_lshlrev_b32_e32 v242, 4, v242
	s_lshl_b32 s25, s9, 9
	v_add_u32_e32 v242, s25, v242
	v_mul_u32_u24_e32 v243, 0x2c00, v241
	v_mul_u32_u24_e32 v244, 0x5800, v241
	v_add_u32_e32 v243, v243, v242
	v_add_u32_e32 v244, v244, v242
	v_lshlrev_b32_e32 v245, 4, v240
	s_lshl_b32 s25, s8, 10
	v_add_u32_e32 v245, s25, v245
	s_mov_b32 m0, s28
	s_nop 0
	global_load_lds_dwordx4 v245, s[10:11]
	s_add_i32 m0, s28, 1024
	s_nop 0
	global_load_lds_dwordx4 v243, s[4:5]
	s_add_i32 m0, s28, 2048
	s_nop 0
	global_load_lds_dwordx4 v244, s[6:7]
	v_add_u32_e32 v245, 0x2c00, v244
	s_add_i32 m0, s28, 3072
	s_nop 0
	global_load_lds_dwordx4 v245, s[6:7]
	v_add_u32_e32 v245, 0xb000, v243
	s_add_i32 m0, s28, 4096
	s_nop 0
	global_load_lds_dwordx4 v245, s[6:7]
	s_add_i32 m0, s28, 5120
	s_nop 0
	global_load_lds_dwordx4 v243, s[14:15]

.LBB0_1871:
	s_add_u32 s10, s70, 0x128000
	s_addc_u32 s11, s71, 0
	s_add_u32 s12, s70, 0x3b00000
	s_addc_u32 s13, s71, 0
	s_lshl_b32 s7, s14, 5
	s_mov_b64 s[14:15], 0x80
	s_and_b32 s24, s7, 0x60
	s_add_i32 m0, s40, 0x18000
	v_lshl_add_u64 v[6:7], v[6:7], 0, s[14:15]
	s_lshl_b32 s17, s16, 13
	s_lshl_b32 s25, s24, 7
	s_waitcnt vmcnt(2)
	s_barrier
	global_load_lds_dwordx4 v[6:7], off
	v_lshl_add_u64 v[4:5], v[4:5], 0, s[14:15]
	s_add_i32 m0, s40, 0x1a000
	s_add_i32 s45, s40, 0x8000
	s_add_i32 s46, s40, 0xa000
	global_load_lds_dwordx4 v[4:5], off
	v_lshl_add_u64 v[0:1], v[0:1], 0, s[14:15]
	s_mov_b32 m0, s45
	s_add_u32 s22, s34, 0x580080
	global_load_lds_dwordx4 v[0:1], off
	v_lshl_add_u64 v[0:1], v[2:3], 0, s[14:15]
	s_mov_b32 m0, s46
	s_addc_u32 s23, s35, 0
	global_load_lds_dwordx4 v[0:1], off
	s_add_i32 m0, s40, 0x1c000
	v_lshl_add_u64 v[0:1], s[22:23], 0, v[148:149]
	global_load_lds_dwordx4 v[0:1], off
	v_lshl_add_u64 v[0:1], s[22:23], 0, v[144:145]
	s_add_i32 m0, s40, 0x1e000
	s_cmpk_lt_u32 s5, 0x100
	global_load_lds_dwordx4 v[0:1], off
	v_lshrrev_b32_e32 v1, 1, v9
	v_and_b32_e32 v1, 24, v1
	v_and_b32_e32 v0, 15, v9
	v_lshlrev_b32_e32 v2, 1, v1
	v_lshl_or_b32 v164, s16, 6, v0
	v_lshl_or_b32 v0, v0, 6, v2
	v_lshlrev_b32_e32 v2, 2, v9
	v_and_b32_e32 v2, 32, v2
	v_bitop3_b32 v3, v0, s17, v2 bitop3:0xde
	v_bitop3_b32 v165, v0, s25, v2 bitop3:0xde
	v_lshlrev_b32_e32 v0, 14, v13
	v_and_b32_e32 v0, 0xffff8000, v0
	v_or_b32_e32 v166, s24, v1
	v_lshl_add_u32 v0, v12, 11, v0
	v_and_b32_e32 v1, 1, v13
	v_lshl_or_b32 v0, v1, 6, v0
	v_lshl_add_u32 v152, v14, 1, v0
	v_lshrrev_b32_e32 v248, 11, v152
	v_and_b32_e32 v249, 0x7ff, v152
	v_and_b32_e32 v250, 15, v248
	v_lshlrev_b32_e32 v250, 2, v250
	v_bfe_u32 v251, v248, 4, 2
	v_and_or_b32 v248, v248, 64, v250
	v_or_b32_e32 v248, v248, v251
	v_lshl_or_b32 v152, v248, 11, v249
	v_lshlrev_b32_e32 v0, 14, v8
	v_and_b32_e32 v0, 0xffff8000, v0
	s_waitcnt vmcnt(6)
	v_lshl_add_u32 v0, v10, 11, v0
	v_and_b32_e32 v1, 1, v8
	s_cselect_b64 s[16:17], -1, 0
	v_lshl_or_b32 v0, v1, 6, v0
	s_add_i32 s47, 0, 0x10000
	s_add_i32 s48, 0, 0x14000
	s_sext_i32_i16 s7, s4
	v_mov_b32_e32 v153, v149
	v_lshl_add_u32 v154, v11, 1, v0
	v_lshrrev_b32_e32 v248, 11, v154
	v_and_b32_e32 v249, 0x7ff, v154
	v_and_b32_e32 v250, 15, v248
	v_lshlrev_b32_e32 v250, 2, v250
	v_bfe_u32 v251, v248, 4, 2
	v_and_or_b32 v248, v248, 64, v250
	v_or_b32_e32 v248, v248, v251
	v_lshl_or_b32 v154, v248, 11, v249
	v_mov_b32_e32 v155, v149
	v_mov_b64_e32 v[156:157], 0x2c0
	v_mov_b64_e32 v[158:159], 0x2bf
	v_add_u32_e32 v167, s47, v165
	v_add_u32_e32 v168, s48, v165
	v_add_u32_e32 v169, 0, v3
	v_mov_b32_e32 v170, 0x358637bd
	s_mov_b32 s49, 0x800000
	s_movk_i32 s51, 0x2c00
	s_barrier
	s_mov_b32 s101, 2
	s_mov_b32 s28, 0x22c00
	v_readfirstlane_b32 s23, v230
	s_cmp_lt_u32 s23, 64
	s_cbranch_scc0 .LpreC_nf
	s_add_i32 s4, s6, 0
	s_ashr_i32 s4, s4, 2
	s_add_i32 s4, s4, 1
	s_cmp_gt_i32 s6, -1
	s_cselect_b32 s4, s4, 0
	s_mul_hi_i32 s5, s4, 0x5800
	s_mulk_i32 s4, 0x5800
	s_add_u32 s4, s33, s4
	s_addc_u32 s5, s50, s5
	v_readlane_b32 s12, v254, 5
	v_readlane_b32 s13, v254, 6
	v_readlane_b32 s26, v254, 7
	v_readlane_b32 s27, v254, 8
	s_nop 0
	s_add_u32 s12, s12, 0x10800
	s_addc_u32 s13, s13, 0
	s_add_u32 s26, s26, 0x5800
	s_addc_u32 s27, s27, 0
	v_and_b32_e32 v240, 63, v230
	v_lshrrev_b32_e32 v241, 5, v240
	v_and_b32_e32 v242, 31, v240
	v_lshlrev_b32_e32 v242, 4, v242
	s_lshl_b32 s23, s7, 9
	v_add_u32_e32 v242, s23, v242
	v_mul_u32_u24_e32 v243, 0x2c00, v241
	v_mul_u32_u24_e32 v244, 0x5800, v241
	v_add_u32_e32 v243, v243, v242
	v_add_u32_e32 v244, v244, v242
	v_lshlrev_b32_e32 v245, 4, v240
	s_lshl_b32 s23, s6, 10
	v_add_u32_e32 v245, s23, v245
	s_mov_b32 m0, s28
	s_nop 0
	global_load_lds_dwordx4 v245, s[10:11]
	s_add_i32 m0, s28, 1024
	s_nop 0
	global_load_lds_dwordx4 v243, s[4:5]
	s_add_i32 m0, s28, 2048
	s_nop 0
	global_load_lds_dwordx4 v244, s[12:13]
	v_add_u32_e32 v245, 0x2c00, v244
	s_add_i32 m0, s28, 3072
	s_nop 0
	global_load_lds_dwordx4 v245, s[12:13]
	v_add_u32_e32 v245, 0xb000, v243
	s_add_i32 m0, s28, 4096
	s_nop 0
	global_load_lds_dwordx4 v245, s[12:13]
	s_add_i32 m0, s28, 5120
	s_nop 0
	global_load_lds_dwordx4 v243, s[26:27]
